# r16 + MLA inner-loop K/V/rope tile loads in saddr+voffset form (10 VALU address ops per two tiles removed)
# speedup vs baseline: 1.0143x; 1.0030x over previous
.Lmla_body:
	s_add_u32 s78, s70, 0xc000000
	s_addc_u32 s79, s71, 0
	s_add_u32 s80, s70, 0xc020000
	s_addc_u32 s81, s71, 0
	s_add_u32 s82, s70, 0x1eba3000
	s_addc_u32 s83, s71, 0
	s_add_u32 s86, s70, 0x1eba4000
	s_addc_u32 s87, s71, 0
	s_cmpk_gt_i32 s12, 0x5ff
	s_waitcnt vmcnt(0)
	v_mbcnt_lo_u32_b32 v0, -1, 0
	v_mbcnt_hi_u32_b32 v0, -1, v0
	s_cbranch_scc1 .LBB0_289
	v_add_u32_e32 v5, s84, v0
	v_ashrrev_i32_e32 v6, 3, v5
	v_and_b32_e32 v12, 0x1fffff0, v6
	v_lshlrev_b32_e32 v13, 1, v6
	v_lshlrev_b32_e32 v7, 3, v5
	v_and_or_b32 v12, v13, 8, v12
	s_add_u32 s16, s70, 0x17a0000
	v_and_b32_e32 v152, 56, v7
	v_and_b32_e32 v8, 24, v7
	v_lshrrev_b32_e32 v12, 2, v12
	v_bfe_u32 v7, v7, 5, 1
	s_addc_u32 s17, s71, 0
	v_lshrrev_b32_e32 v13, 1, v6
	v_or_b32_e32 v7, v12, v7
	v_and_b32_e32 v12, 3, v6
	s_add_u32 s18, s70, 0x77a0000
	v_and_or_b32 v12, v13, 4, v12
	v_lshlrev_b32_e32 v13, 1, v152
	s_addc_u32 s19, s71, 0
	v_and_b32_e32 v14, 48, v13
	s_add_u32 s20, s70, 0xbfa0000
	v_lshl_or_b32 v12, v12, 6, v14
	v_lshlrev_b32_e32 v14, 4, v6
	s_addc_u32 s21, s71, 0
	v_lshl_or_b32 v12, v7, 9, v12
	v_lshlrev_b32_e32 v7, 8, v6
	v_and_b32_e32 v14, 0xf0, v14
	s_add_u32 s22, s70, 0x1eba0000
	v_bfe_u32 v11, v5, 2, 6
	v_bitop3_b32 v193, v13, v7, v14 bitop3:0xde
	v_mov_b32_e32 v14, 0x80
	v_lshlrev_b32_e32 v15, 2, v5
	s_addc_u32 s23, s71, 0
	v_ashrrev_i32_e32 v1, 6, v5
	v_and_b32_e32 v2, 0x3fffffc0, v5
	s_add_i32 s0, 0, 0x12000
	v_lshlrev_b32_e32 v7, 8, v11
	v_lshl_or_b32 v14, v8, 1, v14
	v_and_b32_e32 v15, 0xf0, v15
	v_and_b32_e32 v3, 63, v0
	v_and_b32_e32 v9, 31, v0
	v_lshl_add_u32 v153, v2, 2, s0
	v_lshlrev_b32_e32 v2, 5, v1
	v_bitop3_b32 v194, v14, v7, v15 bitop3:0xde
	v_lshlrev_b32_e32 v14, 4, v0
	v_or_b32_e32 v192, v2, v9
	s_movk_i32 s0, 0x600
	v_lshlrev_b32_e32 v7, 3, v3
	v_and_b32_e32 v15, 0xc0, v14
	v_lshlrev_b32_e32 v16, 1, v0
	v_mad_i64_i32 v[148:149], s[0:1], v192, s0, 0
	v_and_or_b32 v15, v7, 24, v15
	v_and_b32_e32 v16, 32, v16
	v_and_b32_e32 v7, 0x100, v7
	s_cmp_lg_u32 0, -1
	v_bfe_u32 v10, v0, 5, 1
	v_or3_b32 v7, v15, v16, v7
	s_cselect_b32 s0, 0, 0
	v_add_u32_e32 v195, s0, v7
	v_ashrrev_i32_e32 v7, 31, v6
	v_lshlrev_b32_e32 v197, 4, v10
	v_lshlrev_b64 v[154:155], 11, v[6:7]
	v_add_u32_e32 v196, 0, v12
	v_lshlrev_b32_e32 v7, 8, v9
	v_and_b32_e32 v12, 0xf0, v14
	v_or_b32_e32 v14, 32, v197
	v_bitop3_b32 v199, v14, v7, v12 bitop3:0xde
	v_or_b32_e32 v14, 64, v197
	v_bitop3_b32 v200, v14, v7, v12 bitop3:0xde
	v_or_b32_e32 v14, 0x60, v197
	v_bitop3_b32 v201, v14, v7, v12 bitop3:0xde
	v_or_b32_e32 v14, 0x80, v197
	s_mov_b64 s[0:1], 0x20000
	v_bitop3_b32 v202, v14, v7, v12 bitop3:0xde
	v_or_b32_e32 v14, 0xa0, v197
	s_add_i32 s2, 0, 0x12800
	v_lshl_add_u64 v[156:157], v[154:155], 0, s[0:1]
	v_bitop3_b32 v198, v197, v7, v12 bitop3:0xde
	v_bitop3_b32 v203, v14, v7, v12 bitop3:0xde
	v_cmp_gt_u32_e64 s[0:1], 32, v3
	v_lshl_add_u32 v1, v1, 12, s2
	v_lshlrev_b32_e32 v3, 9, v10
	v_lshlrev_b32_e32 v7, 1, v9
	v_add3_u32 v205, v1, v3, v7
	v_ashrrev_i32_e32 v3, 31, v2
	v_lshlrev_b64 v[160:161], 11, v[2:3]
	v_bfe_u32 v3, v0, 3, 3
	v_add_u32_e32 v7, v1, v13
	v_or_b32_e32 v1, 8, v3
	v_lshlrev_b32_e32 v4, 3, v10
	v_lshlrev_b32_e32 v13, 7, v1
	v_lshlrev_b32_e32 v10, 10, v1
	v_or_b32_e32 v1, 16, v3
	v_mov_b32_e32 v151, 0
	v_lshlrev_b32_e32 v15, 7, v1
	v_lshlrev_b32_e32 v12, 10, v1
	v_or_b32_e32 v1, 24, v3
	v_and_b32_e32 v150, 32, v0
	v_lshl_add_u32 v204, v9, 2, v153
	v_lshlrev_b32_e32 v9, 7, v3
	v_lshlrev_b32_e32 v2, 10, v3
	v_lshlrev_b32_e32 v3, 7, v1
	v_lshlrev_b32_e32 v14, 10, v1
	v_lshl_add_u64 v[0:1], s[70:71], 0, v[150:151]
	s_mov_b64 s[6:7], 0x16a0000
	v_lshl_add_u64 v[162:163], v[0:1], 0, s[6:7]
	s_mov_b64 s[6:7], 0x1720000
	v_lshl_add_u64 v[164:165], v[0:1], 0, s[6:7]
	v_and_b32_e32 v0, 3, v5
	v_lshlrev_b32_e32 v0, 4, v0
	v_lshlrev_b32_e32 v6, 5, v11
	s_mov_b64 s[4:5], 0x40000
	v_lshl_or_b32 v166, v11, 6, v0
	v_lshlrev_b32_e32 v0, 4, v5
	s_movk_i32 s2, 0x70
	s_mov_b32 s3, 0
	v_lshl_add_u64 v[158:159], v[154:155], 0, s[4:5]
	v_mov_b32_e32 v167, v151
	v_and_or_b32 v168, v0, s2, v154
	v_mov_b32_e32 v169, v155
	s_movk_i32 s24, 0x2000
	s_mov_b32 s25, 0x41000000
	s_mov_b64 s[6:7], 0x2000
	v_add_u32_e32 v206, v7, v9
	v_lshlrev_b32_e32 v170, 1, v2
	v_add_u32_e32 v207, v7, v13
	v_lshlrev_b32_e32 v172, 1, v10
	v_add_u32_e32 v208, v7, v15
	v_lshlrev_b32_e32 v174, 1, v12
	v_add_u32_e32 v209, v7, v3
	v_lshlrev_b32_e32 v176, 1, v14
	v_lshlrev_b32_e32 v178, 1, v4
	v_lshlrev_b32_e32 v180, 1, v6
	v_lshlrev_b32_e32 v182, 1, v8
	s_mov_b32 s26, s12
	s_branch .LBB0_258

.LBB0_263:
	s_mov_b32 s29, s28
	s_mov_b32 s28, s52
	s_barrier
	s_lshl_b32 s30, s29, 14
	s_add_i32 s30, s30, 0
	v_add_u32_e32 v36, s30, v198
	ds_read_b128 v[32:35], v36 offset:24576
	ds_read_b128 v[36:39], v36 offset:32768
	v_add_u32_e32 v40, s30, v199
	v_add_u32_e32 v44, s30, v200
	v_add_u32_e32 v173, s30, v201
	s_waitcnt lgkmcnt(1)
	v_mfma_f32_32x32x16_bf16 v[96:111], v[32:35], v[116:119], v[48:63]
	ds_read_b128 v[32:35], v40 offset:24576
	ds_read_b128 v[40:43], v40 offset:32768
	v_add_u32_e32 v177, s30, v202
	v_exp_f32_e32 v64, v64
	v_exp_f32_e32 v65, v65
	v_exp_f32_e32 v66, v66
	v_exp_f32_e32 v67, v67
	v_exp_f32_e32 v68, v68
	s_waitcnt lgkmcnt(2)
	v_mfma_f32_32x32x16_bf16 v[80:95], v[36:39], v[116:119], v[48:63]
	ds_read_b128 v[36:39], v44 offset:24576
	ds_read_b128 v[44:47], v44 offset:32768
	ds_read_b128 v[224:227], v173 offset:24576
	ds_read_b128 v[228:231], v173 offset:32768
	ds_read_b128 v[232:235], v177 offset:24576
	ds_read_b128 v[236:239], v177 offset:32768
	v_exp_f32_e32 v69, v69
	v_add_u32_e32 v179, s30, v203
	s_waitcnt lgkmcnt(7)
	v_mfma_f32_32x32x16_bf16 v[96:111], v[32:35], v[112:115], v[96:111]
	ds_read_b128 v[32:35], v179 offset:24576
	ds_read_b128 v[240:243], v179 offset:32768
	s_waitcnt lgkmcnt(8)
	v_mfma_f32_32x32x16_bf16 v[80:95], v[40:43], v[112:115], v[80:95]
	v_exp_f32_e32 v40, v70
	v_exp_f32_e32 v41, v71
	v_exp_f32_e32 v42, v72
	v_exp_f32_e32 v43, v73
	v_exp_f32_e32 v70, v74
	v_exp_f32_e32 v71, v75
	v_exp_f32_e32 v72, v76
	s_waitcnt lgkmcnt(7)
	v_mfma_f32_32x32x16_bf16 v[96:111], v[36:39], v[124:127], v[96:111]
	v_add_f32_e32 v36, 0, v215
	v_add_f32_e32 v36, v219, v36
	v_add_f32_e32 v36, v216, v36
	v_add_f32_e32 v36, v220, v36
	v_add_f32_e32 v36, v217, v36
	v_add_f32_e32 v36, v221, v36
	v_add_f32_e32 v36, v218, v36
	s_waitcnt lgkmcnt(6)
	v_mfma_f32_32x32x16_bf16 v[80:95], v[44:47], v[124:127], v[80:95]
	v_add_f32_e32 v36, v222, v36
	v_add_f32_e32 v36, v188, v36
	v_add_f32_e32 v36, v211, v36
	v_add_f32_e32 v36, v189, v36
	v_add_f32_e32 v36, v212, v36
	v_add_f32_e32 v36, v190, v36
	v_add_f32_e32 v36, v213, v36
	s_waitcnt lgkmcnt(5)
	v_mfma_f32_32x32x16_bf16 v[96:111], v[224:227], v[120:123], v[96:111]
	v_add_f32_e32 v36, v191, v36
	v_add_f32_e32 v36, v214, v36
	v_add_f32_e32 v36, v64, v36
	v_add_f32_e32 v36, v65, v36
	v_add_f32_e32 v36, v66, v36
	v_add_f32_e32 v36, v67, v36
	v_add_f32_e32 v36, v68, v36
	s_waitcnt lgkmcnt(4)
	v_mfma_f32_32x32x16_bf16 v[80:95], v[228:231], v[120:123], v[80:95]
	v_add_f32_e32 v36, v69, v36
	v_add_f32_e32 v36, v40, v36
	v_add_f32_e32 v36, v41, v36
	v_add_f32_e32 v36, v42, v36
	v_exp_f32_e32 v73, v77
	v_add_f32_e32 v36, v43, v36
	v_exp_f32_e32 v74, v78
	s_waitcnt lgkmcnt(3)
	v_mfma_f32_32x32x16_bf16 v[96:111], v[232:235], v[132:135], v[96:111]
	v_add_f32_e32 v36, v70, v36
	v_exp_f32_e32 v75, v79
	v_add_f32_e32 v36, v71, v36
	v_add_f32_e32 v36, v72, v36
	v_add_f32_e32 v36, v73, v36
	v_add_f32_e32 v36, v74, v36
	v_add_f32_e32 v177, v75, v36
	s_waitcnt lgkmcnt(2)
	v_mfma_f32_32x32x16_bf16 v[80:95], v[236:239], v[132:135], v[80:95]
	v_mov_b32_e32 v179, v177
	v_cvt_pk_bf16_f32 v36, v215, v219
	v_cvt_pk_bf16_f32 v37, v216, v220
	v_cvt_pk_bf16_f32 v38, v217, v221
	v_cvt_pk_bf16_f32 v39, v218, v222
	v_cvt_pk_bf16_f32 v44, v64, v65
	v_cvt_pk_bf16_f32 v45, v66, v67
	s_waitcnt lgkmcnt(1)
	v_mfma_f32_32x32x16_bf16 v[96:111], v[32:35], v[128:131], v[96:111]
	v_cvt_pk_bf16_f32 v32, v188, v211
	v_cvt_pk_bf16_f32 v33, v189, v212
	v_cvt_pk_bf16_f32 v34, v190, v213
	v_cvt_pk_bf16_f32 v35, v191, v214
	v_cvt_pk_bf16_f32 v46, v68, v69
	v_cvt_pk_bf16_f32 v47, v40, v41
	v_cvt_pk_bf16_f32 v40, v42, v43
	s_waitcnt lgkmcnt(0)
	v_mfma_f32_32x32x16_bf16 v[80:95], v[240:243], v[128:131], v[80:95]
	v_cvt_pk_bf16_f32 v41, v70, v71
	v_cvt_pk_bf16_f32 v42, v72, v73
	v_cvt_pk_bf16_f32 v43, v74, v75
	v_permlane32_swap_b32_e32 v177, v179
	v_permlane32_swap_b32_e32 v36, v38
	v_permlane32_swap_b32_e32 v37, v39
	v_permlane32_swap_b32_e32 v32, v34
	v_permlane32_swap_b32_e32 v33, v35
	v_permlane32_swap_b32_e32 v44, v46
	v_permlane32_swap_b32_e32 v45, v47
	v_permlane32_swap_b32_e32 v40, v42
	v_permlane32_swap_b32_e32 v41, v43
	s_lshl_b32 s30, s9, 13
	s_lshl_b32 s31, s9, 14
	s_waitcnt vmcnt(0)
	v_add_u32_e32 v64, s30, v196
	s_add_i32 s33, s31, 0
	s_waitcnt vmcnt(0)
	ds_write_b128 v64, v[136:139]
	v_add_u32_e32 v64, s33, v193
	s_add_i32 s31, s2, 1
	ds_write_b128 v64, v[140:143] offset:24576
	v_add_u32_e32 v64, s33, v194
	s_cmp_ge_u32 s31, s27
	ds_write_b128 v64, v[144:147] offset:24576
	s_cbranch_scc1 .LBB0_265
	s_nop 1
	global_load_dwordx4 v[136:139], v186, s[78:79] offset:128
	global_load_dwordx4 v[140:143], v186, s[78:79]
	s_nop 1
	global_load_dwordx4 v[144:147], v184, s[82:83]

.LBB0_270:
	v_exp_f32_e32 v218, v96
	v_exp_f32_e32 v219, v97
	v_exp_f32_e32 v220, v98
	v_exp_f32_e32 v221, v99
	v_exp_f32_e32 v222, v100
	v_exp_f32_e32 v223, v101
	v_exp_f32_e32 v224, v102
	v_exp_f32_e32 v225, v103
	v_exp_f32_e32 v226, v104
	v_exp_f32_e32 v227, v105
	v_exp_f32_e32 v228, v106
	v_exp_f32_e32 v229, v107
	v_exp_f32_e32 v230, v108
	v_exp_f32_e32 v231, v109
	v_exp_f32_e32 v232, v110
	v_exp_f32_e32 v233, v111
	s_waitcnt lgkmcnt(0)
	s_barrier
	v_add_u32_e32 v68, s33, v198
	ds_read_b128 v[64:67], v68 offset:24576
	ds_read_b128 v[210:213], v68 offset:32768
	v_add_u32_e32 v183, s33, v199
	v_exp_f32_e32 v87, v87
	v_exp_f32_e32 v88, v88
	s_waitcnt lgkmcnt(1)
	v_mfma_f32_32x32x16_bf16 v[96:111], v[64:67], v[116:119], v[32:47]
	v_exp_f32_e32 v89, v89
	v_exp_f32_e32 v90, v90
	v_exp_f32_e32 v91, v91
	v_exp_f32_e32 v234, v92
	v_exp_f32_e32 v235, v93
	v_exp_f32_e32 v236, v94
	v_exp_f32_e32 v237, v95
	s_waitcnt lgkmcnt(0)
	v_mfma_f32_32x32x16_bf16 v[64:79], v[210:213], v[116:119], v[32:47]
	ds_read_b128 v[210:213], v183 offset:24576
	ds_read_b128 v[214:217], v183 offset:32768
	v_add_u32_e32 v183, s33, v200
	v_cvt_pk_bf16_f32 v92, v218, v219
	v_cvt_pk_bf16_f32 v93, v220, v221
	v_cvt_pk_bf16_f32 v94, v222, v223
	v_cvt_pk_bf16_f32 v95, v224, v225
	s_waitcnt lgkmcnt(1)
	v_mfma_f32_32x32x16_bf16 v[96:111], v[210:213], v[112:115], v[96:111]
	v_permlane32_swap_b32_e32 v92, v94
	v_permlane32_swap_b32_e32 v93, v95
	s_waitcnt lgkmcnt(0)
	v_mfma_f32_32x32x16_bf16 v[64:79], v[214:217], v[112:115], v[64:79]
	ds_read_b128 v[210:213], v183 offset:24576
	ds_read_b128 v[214:217], v183 offset:32768
	v_add_u32_e32 v183, s33, v201
	s_waitcnt lgkmcnt(1)
	v_mfma_f32_32x32x16_bf16 v[96:111], v[210:213], v[124:127], v[96:111]
	s_waitcnt lgkmcnt(0)
	v_mfma_f32_32x32x16_bf16 v[64:79], v[214:217], v[124:127], v[64:79]
	ds_read_b128 v[210:213], v183 offset:24576
	ds_read_b128 v[214:217], v183 offset:32768
	v_add_u32_e32 v183, s33, v202
	s_waitcnt lgkmcnt(1)
	v_mfma_f32_32x32x16_bf16 v[96:111], v[210:213], v[120:123], v[96:111]
	s_waitcnt lgkmcnt(0)
	v_mfma_f32_32x32x16_bf16 v[64:79], v[214:217], v[120:123], v[64:79]
	ds_read_b128 v[210:213], v183 offset:24576
	ds_read_b128 v[214:217], v183 offset:32768
	v_add_u32_e32 v183, s33, v203
	s_waitcnt lgkmcnt(1)
	v_mfma_f32_32x32x16_bf16 v[96:111], v[210:213], v[132:135], v[96:111]
	s_waitcnt lgkmcnt(0)
	v_mfma_f32_32x32x16_bf16 v[64:79], v[214:217], v[132:135], v[64:79]
	ds_read_b128 v[210:213], v183 offset:24576
	ds_read_b128 v[214:217], v183 offset:32768
	s_waitcnt lgkmcnt(1)
	v_mfma_f32_32x32x16_bf16 v[96:111], v[210:213], v[128:131], v[96:111]
	v_exp_f32_e32 v211, v80
	v_add_f32_e32 v80, 0, v218
	v_add_f32_e32 v80, v219, v80
	v_add_f32_e32 v80, v220, v80
	v_add_f32_e32 v80, v221, v80
	v_add_f32_e32 v80, v222, v80
	v_add_f32_e32 v80, v223, v80
	v_add_f32_e32 v80, v224, v80
	v_add_f32_e32 v80, v225, v80
	v_add_f32_e32 v80, v226, v80
	v_add_f32_e32 v80, v227, v80
	v_add_f32_e32 v80, v228, v80
	v_add_f32_e32 v80, v229, v80
	v_add_f32_e32 v80, v230, v80
	v_exp_f32_e32 v212, v81
	v_add_f32_e32 v80, v231, v80
	v_exp_f32_e32 v213, v82
	v_add_f32_e32 v80, v232, v80
	s_waitcnt lgkmcnt(0)
	v_mfma_f32_32x32x16_bf16 v[64:79], v[214:217], v[128:131], v[64:79]
	v_exp_f32_e32 v214, v83
	v_add_f32_e32 v80, v233, v80
	v_exp_f32_e32 v215, v84
	v_add_f32_e32 v80, v211, v80
	v_exp_f32_e32 v216, v85
	v_add_f32_e32 v80, v212, v80
	v_exp_f32_e32 v217, v86
	v_add_f32_e32 v80, v213, v80
	v_add_f32_e32 v80, v214, v80
	v_add_f32_e32 v80, v215, v80
	v_add_f32_e32 v80, v216, v80
	v_add_f32_e32 v80, v217, v80
	v_add_f32_e32 v80, v87, v80
	v_add_f32_e32 v80, v88, v80
	v_add_f32_e32 v80, v89, v80
	v_add_f32_e32 v80, v90, v80
	v_add_f32_e32 v80, v91, v80
	v_add_f32_e32 v80, v234, v80
	v_add_f32_e32 v80, v235, v80
	v_add_f32_e32 v80, v236, v80
	v_add_f32_e32 v183, v237, v80
	v_mov_b32_e32 v210, v183
	v_cvt_pk_bf16_f32 v80, v226, v227
	v_cvt_pk_bf16_f32 v81, v228, v229
	v_cvt_pk_bf16_f32 v82, v230, v231
	v_cvt_pk_bf16_f32 v83, v232, v233
	v_cvt_pk_bf16_f32 v84, v211, v212
	v_cvt_pk_bf16_f32 v85, v213, v214
	v_cvt_pk_bf16_f32 v86, v215, v216
	v_cvt_pk_bf16_f32 v87, v217, v87
	v_cvt_pk_bf16_f32 v88, v88, v89
	v_cvt_pk_bf16_f32 v89, v90, v91
	v_cvt_pk_bf16_f32 v90, v234, v235
	v_cvt_pk_bf16_f32 v91, v236, v237
	s_nop 1
	v_permlane32_swap_b32_e32 v183, v210
	v_permlane32_swap_b32_e32 v80, v82
	v_permlane32_swap_b32_e32 v81, v83
	v_permlane32_swap_b32_e32 v84, v86
	v_permlane32_swap_b32_e32 v85, v87
	v_permlane32_swap_b32_e32 v88, v90
	v_permlane32_swap_b32_e32 v89, v91
	v_add_u32_e32 v211, s31, v196
	s_lshl_b32 s31, s28, 14
	s_add_i32 s31, s31, 0
	s_add_i32 s2, s2, 2
	s_waitcnt vmcnt(0)
	s_cmp_ge_u32 s2, s27
	s_waitcnt vmcnt(2)
	ds_write_b128 v211, v[136:139]
	v_add_u32_e32 v211, s31, v193
	s_cselect_b64 s[52:53], -1, 0
	s_waitcnt vmcnt(1)
	ds_write_b128 v211, v[140:143] offset:24576
	v_add_u32_e32 v211, s31, v194
	s_and_b64 vcc, exec, s[52:53]
	s_waitcnt vmcnt(0)
	ds_write_b128 v211, v[144:147] offset:24576
	s_cbranch_vccnz .LBB0_272
	s_nop 1
	global_load_dwordx4 v[136:139], v186, s[80:81] offset:128
	s_nop 0
	global_load_dwordx4 v[140:143], v186, s[80:81]
	global_load_dwordx4 v[144:147], v184, s[86:87]
